# hand-written ffn-up epilogue: DPP-fused conv taps, packed f32 gelu, 916 instead of 2005 lines per unit
# speedup vs baseline: 1.0258x; 1.0188x over previous
;     __device__ __forceinline__ void operator()(const f32x4 (&acc)[2][2][4][2], const Unit& u, int wr, int wc, int fr, int fq) const {
;         EPI_LAUNDER const int cb = wc * 32 + 8 * fq, c0 = u.pn * HALF + cb, tid = (wr * 4 + wc) * 64 + fq * 16 + fr;
;         PG8_LAS float* RST = xch + 1024;
;         if (tid < 256) RST[tid] = rstd16(rsx, u.pm * BM + tid, 1.f / 1024.f);
; #pragma unroll
;         for (int ai = 0; ai < 2; ++ai) if (fr >= 14) { PG8_LAS float* p = xch + ((2 * ai + wr) * 2 + (fr - 14)) * 128 + cb; *(PG8_LAS f32x4*)p = acc[ai][1][3][0]; *(PG8_LAS f32x4*)(p + 4) = acc[ai][1][3][1]; }
;         f32x4 w0[2], w1[2], w2[2], bb[2];
; #pragma unroll
;         for (int n = 0; n < 2; ++n) { w0[n] = *(const f32x4*)(cw + c0 + 4 * n); w1[n] = *(const f32x4*)(cw + DFF + c0 + 4 * n); w2[n] = *(const f32x4*)(cw + 2 * DFF + c0 + 4 * n); bb[n] = *(const f32x4*)(cbias + c0 + 4 * n); }
;         asm volatile("s_waitcnt lgkmcnt(0)" ::: "memory"); __builtin_amdgcn_s_barrier(); asm volatile("" ::: "memory");
; #pragma unroll
;         for (int ai = 0; ai < 2; ++ai) { const int bnd = 2 * ai + wr;
;             f32x4 hp0[2], hp1[2], gp[2];
;             { const int pb_ = bnd > 0 ? bnd - 1 : 0; const float r0 = bnd > 0 ? RST[64 * bnd - 2] : 0.f, r1 = bnd > 0 ? RST[64 * bnd - 1] : 0.f;
; #pragma unroll
;               for (int n = 0; n < 2; ++n) { hp0[n] = *(const PG8_LAS f32x4*)(xch + (pb_ * 2 + 0) * 128 + cb + 4 * n) * r0; hp1[n] = *(const PG8_LAS f32x4*)(xch + (pb_ * 2 + 1) * 128 + cb + 4 * n) * r1; gp[n] = hp0[n]; } }
; #pragma unroll
;             for (int m = 0; m < 4; ++m) { const int rit = ai * HALF + wr * 64 + m * 16 + fr, row = u.pm * BM + rit; const float r = RST[rit];
;                 f32x4 g[2], vv[2], hv[2];
; #pragma unroll
;                 for (int n = 0; n < 2; ++n) { g[n] = acc[ai][1][m][n] * r; vv[n] = acc[ai][0][m][n] * r;
; #pragma unroll
;                     for (int e = 0; e < 4; ++e) { const float a1 = dpp_mov<0x121>(g[n][e]), a2 = dpp_mov<0x122>(g[n][e]);
;                         const float b1 = m == 0 ? hp1[n][e] : dpp_mov<0x121>(gp[n][e]), b2 = m == 0 ? (fr == 1 ? hp1[n][e] : hp0[n][e]) : dpp_mov<0x122>(gp[n][e]);
;                         const float p1 = fr >= 1 ? a1 : b1, p2 = fr >= 2 ? a2 : b2;
;                         const float cv = bb[n][e] + w0[n][e] * p2 + w1[n][e] * p1 + w2[n][e] * g[n][e];
.LBB0_2035:
	s_or_b64 exec, exec, s[8:9]
	v_lshl_add_u32 v174, s12, 7, v0
	v_ashrrev_i32_e32 v175, 31, v174
	v_lshlrev_b64 v[192:193], 2, v[174:175]
	v_lshl_add_u64 v[38:39], s[2:3], 0, v[192:193]
	v_lshl_add_u64 v[40:41], s[62:63], 0, v[192:193]
	v_lshl_add_u64 v[54:55], s[96:97], 0, v[192:193]
	v_lshl_add_u64 v[56:57], s[18:19], 0, v[192:193]
	global_load_dwordx4 v[34:37], v[38:39], off offset:16
	global_load_dwordx4 v[50:53], v[38:39], off
	global_load_dwordx4 v[146:149], v[40:41], off offset:16
	global_load_dwordx4 v[158:161], v[40:41], off
	global_load_dwordx4 v[150:153], v[54:55], off offset:16
	global_load_dwordx4 v[154:157], v[54:55], off
	s_nop 0
	global_load_dwordx4 v[38:41], v[56:57], off offset:16
	s_nop 0
	global_load_dwordx4 v[54:57], v[56:57], off
	s_waitcnt lgkmcnt(0)
	s_barrier
	v_readlane_b32 s16, v255, 2
	v_cmp_eq_u32_e64 s[6:7], 15, v200
	v_cmp_lt_u32_e64 s[8:9], 13, v200
	v_cmp_eq_u32_e64 s[10:11], 14, v200
	v_cmp_gt_u32_e64 s[48:49], 2, v200
	v_mov_b32_e32 v232, 0xc0135761
	v_mov_b32_e32 v233, 0xc0135761
	v_mov_b32_e32 v234, 0xbdd2d3e8
	v_mov_b32_e32 v235, 0xbdd2d3e8
	v_mov_b32_e32 v218, 1.0
	v_mov_b32_e32 v219, 1.0
	v_or_b32_e32 v197, s16, v200
	v_lshl_add_u32 v197, v197, 2, s34
	s_lshl_b32 s17, s40, 8
	s_add_i32 s17, s17, s16
	v_add_u32_e32 v0, s17, v200
	v_mov_b64_e32 v[238:239], s[36:37]
	s_movk_i32 s41, 0x1600
	v_mad_u64_u32 v[238:239], vcc, v0, s41, v[238:239]
	v_lshl_add_u64 v[238:239], v[174:175], 1, v[238:239]
	s_mov_b32 s14, 0x16000
	s_mov_b32 s15, 0
	s_waitcnt vmcnt(0)
	s_cmp_lg_u32 s16, 0
	s_cbranch_scc1 .Lefu_halo0
	v_mov_b32_e32 v202, 0
	v_mov_b32_e32 v210, 0
	v_mov_b32_e32 v203, 0
	v_mov_b32_e32 v211, 0
	v_mov_b32_e32 v204, 0
	v_mov_b32_e32 v212, 0
	v_mov_b32_e32 v205, 0
	v_mov_b32_e32 v213, 0
	v_mov_b32_e32 v206, 0
	v_mov_b32_e32 v214, 0
	v_mov_b32_e32 v207, 0
	v_mov_b32_e32 v215, 0
	v_mov_b32_e32 v208, 0
	v_mov_b32_e32 v216, 0
	v_mov_b32_e32 v209, 0
	v_mov_b32_e32 v217, 0
	s_branch .Lefu_halo0_done
.Lefu_halo0:
	s_lshl_b32 s17, s16, 4
	s_add_i32 s17, s17, s34
	s_add_i32 s17, s17, -5120
	v_add_u32_e32 v198, s17, v199
	s_lshl_b32 s17, s16, 2
	s_add_i32 s17, s17, s34
	s_add_i32 s17, s17, -8
	v_mov_b32_e32 v0, s17
	ds_read_b128 v[210:213], v198
	ds_read_b128 v[214:217], v198 offset:16
	ds_read_b128 v[202:205], v198 offset:512
	ds_read_b128 v[206:209], v198 offset:528
	ds_read_b64 v[176:177], v0
	s_waitcnt lgkmcnt(0)
	v_pk_mul_f32 v[210:211], v[210:211], v[176:177] op_sel_hi:[1,0]
	v_pk_mul_f32 v[212:213], v[212:213], v[176:177] op_sel_hi:[1,0]
	v_pk_mul_f32 v[214:215], v[214:215], v[176:177] op_sel_hi:[1,0]
	v_pk_mul_f32 v[216:217], v[216:217], v[176:177] op_sel_hi:[1,0]
	v_mul_f32_e32 v202, v177, v202
	v_mul_f32_e32 v203, v177, v203
	v_mul_f32_e32 v204, v177, v204
	v_mul_f32_e32 v205, v177, v205
	v_mul_f32_e32 v206, v177, v206
	v_mul_f32_e32 v207, v177, v207
	v_mul_f32_e32 v208, v177, v208
	v_mul_f32_e32 v209, v177, v209
	v_cndmask_b32_e64 v210, v202, v210, s[10:11]
	v_cndmask_b32_e64 v211, v203, v211, s[10:11]
	v_cndmask_b32_e64 v212, v204, v212, s[10:11]
	v_cndmask_b32_e64 v213, v205, v213, s[10:11]
	v_cndmask_b32_e64 v214, v206, v214, s[10:11]
	v_cndmask_b32_e64 v215, v207, v215, s[10:11]
	v_cndmask_b32_e64 v216, v208, v216, s[10:11]
	v_cndmask_b32_e64 v217, v209, v217, s[10:11]
.Lefu_halo0_done:
	ds_read_b32 v176, v197 offset:0
	s_waitcnt lgkmcnt(0)
	v_pk_mul_f32 v[138:139], v[138:139], v[176:177] op_sel_hi:[1,0]
	v_pk_mul_f32 v[140:141], v[140:141], v[176:177] op_sel_hi:[1,0]
	v_pk_mul_f32 v[130:131], v[130:131], v[176:177] op_sel_hi:[1,0]
	v_pk_mul_f32 v[132:133], v[132:133], v[176:177] op_sel_hi:[1,0]
	v_pk_mul_f32 v[142:143], v[142:143], v[176:177] op_sel_hi:[1,0]
	v_pk_mul_f32 v[144:145], v[144:145], v[176:177] op_sel_hi:[1,0]
	v_pk_mul_f32 v[134:135], v[134:135], v[176:177] op_sel_hi:[1,0]
	v_pk_mul_f32 v[136:137], v[136:137], v[176:177] op_sel_hi:[1,0]
	v_cndmask_b32_e64 v202, v138, v202, s[6:7]
	v_cndmask_b32_e64 v203, v139, v203, s[6:7]
	v_cndmask_b32_e64 v204, v140, v204, s[6:7]
	v_cndmask_b32_e64 v205, v141, v205, s[6:7]
	v_cndmask_b32_e64 v206, v130, v206, s[6:7]
	v_cndmask_b32_e64 v207, v131, v207, s[6:7]
	v_cndmask_b32_e64 v208, v132, v208, s[6:7]
	v_cndmask_b32_e64 v209, v133, v209, s[6:7]
	v_cndmask_b32_e64 v210, v138, v210, s[8:9]
	v_cndmask_b32_e64 v211, v139, v211, s[8:9]
	v_cndmask_b32_e64 v212, v140, v212, s[8:9]
	v_cndmask_b32_e64 v213, v141, v213, s[8:9]
	v_cndmask_b32_e64 v214, v130, v214, s[8:9]
	v_cndmask_b32_e64 v215, v131, v215, s[8:9]
	v_cndmask_b32_e64 v216, v132, v216, s[8:9]
	v_cndmask_b32_e64 v217, v133, v217, s[8:9]
	v_pk_fma_f32 v[178:179], v[154:155], v[138:139], v[54:55]
	v_pk_fma_f32 v[180:181], v[156:157], v[140:141], v[56:57]
	v_pk_fma_f32 v[182:183], v[150:151], v[130:131], v[38:39]
	v_pk_fma_f32 v[184:185], v[152:153], v[132:133], v[40:41]
	v_fmac_f32_dpp v178, v202, v158 row_ror:1 row_mask:0xf bank_mask:0xf
	v_fmac_f32_dpp v179, v203, v159 row_ror:1 row_mask:0xf bank_mask:0xf
	v_fmac_f32_dpp v180, v204, v160 row_ror:1 row_mask:0xf bank_mask:0xf
	v_fmac_f32_dpp v181, v205, v161 row_ror:1 row_mask:0xf bank_mask:0xf
	v_fmac_f32_dpp v182, v206, v146 row_ror:1 row_mask:0xf bank_mask:0xf
	v_fmac_f32_dpp v183, v207, v147 row_ror:1 row_mask:0xf bank_mask:0xf
	v_fmac_f32_dpp v184, v208, v148 row_ror:1 row_mask:0xf bank_mask:0xf
	v_fmac_f32_dpp v185, v209, v149 row_ror:1 row_mask:0xf bank_mask:0xf
	v_fmac_f32_dpp v178, v210, v50 row_ror:2 row_mask:0xf bank_mask:0xf
	v_fmac_f32_dpp v179, v211, v51 row_ror:2 row_mask:0xf bank_mask:0xf
	v_fmac_f32_dpp v180, v212, v52 row_ror:2 row_mask:0xf bank_mask:0xf
	v_fmac_f32_dpp v181, v213, v53 row_ror:2 row_mask:0xf bank_mask:0xf
; __device__ __forceinline__ void st16_wt(void* p, u32x4 v) { asm volatile("global_store_dwordx4 %0, %1, off sc1\n\ts_nop 1" :: "v"(p), "v"(v) : "memory"); }
; __device__ __forceinline__ void st16_wt(void* p, f32x4 v) { asm volatile("global_store_dwordx4 %0, %1, off sc1\n\ts_nop 1" :: "v"(p), "v"(v) : "memory"); }
; __device__ __forceinline__ u32x4 pack8(const f32x4& a, const f32x4& b) { u32x4 w; w.x = cvt_pk_bf16(a[0], a[1]); w.y = cvt_pk_bf16(a[2], a[3]); w.z = cvt_pk_bf16(b[0], b[1]); w.w = cvt_pk_bf16(b[2], b[3]); return w; }
;     __device__ __forceinline__ void operator()(const f32x4 (&acc)[2][2][4][2], const Unit& u, int wr, int wc, int fr, int fq) const {
;     ...
;             for (int m = 0; m < 4; ++m) { const int rit = ai * HALF + wr * 64 + m * 16 + fr, row = u.pm * BM + rit; const float r = RST[rit];
;                 f32x4 g[2], vv[2], hv[2];
; #pragma unroll
;                 for (int n = 0; n < 2; ++n) { g[n] = acc[ai][1][m][n] * r; vv[n] = acc[ai][0][m][n] * r;
; #pragma unroll
;                     for (int e = 0; e < 4; ++e) { const float a1 = dpp_mov<0x121>(g[n][e]), a2 = dpp_mov<0x122>(g[n][e]);
;                         const float b1 = m == 0 ? hp1[n][e] : dpp_mov<0x121>(gp[n][e]), b2 = m == 0 ? (fr == 1 ? hp1[n][e] : hp0[n][e]) : dpp_mov<0x122>(gp[n][e]);
;                         const float p1 = fr >= 1 ? a1 : b1, p2 = fr >= 2 ? a2 : b2;
;                         const float cv = bb[n][e] + w0[n][e] * p2 + w1[n][e] * p1 + w2[n][e] * g[n][e];
;                         hv[n][e] = fgelu(cv) * vv[n][e]; } }
;                 if (m == 0 && bnd == 0 && fr < 2) { float* p = fv + ((size_t)u.pm * 2 + fr) * DFF + c0; st16_wt(p, vv[0]); st16_wt(p + 4, vv[1]); float* q = fg + ((size_t)u.pm * 2 + fr) * DFF + c0; st16_wt(q, g[0]); st16_wt(q + 4, g[1]); }
;                 else st16_wt(h + (size_t)row * DFF + c0, pack8(hv[0], hv[1]));
;                 if (m == 3 && bnd == 3 && fr >= 14) { float* p = lg + ((size_t)u.pm * 2 + (fr - 14)) * DFF + c0; st16_wt(p, g[0]); st16_wt(p + 4, g[1]);
;                     if ((u.pm & 7) == 7) { float* q = convout + ((size_t)(u.pm >> 3) * 2 + (fr - 14)) * DFF + c0; *(f32x4*)q = g[0]; *(f32x4*)(q + 4) = g[1]; } }
;                 gp[0] = g[0]; gp[1] = g[1];
;                 asm volatile("" ::: "memory"); }
	v_fmac_f32_dpp v182, v214, v34 row_ror:2 row_mask:0xf bank_mask:0xf
	v_fmac_f32_dpp v183, v215, v35 row_ror:2 row_mask:0xf bank_mask:0xf
	v_fmac_f32_dpp v184, v216, v36 row_ror:2 row_mask:0xf bank_mask:0xf
	v_fmac_f32_dpp v185, v217, v37 row_ror:2 row_mask:0xf bank_mask:0xf
	v_pk_mul_f32 v[222:223], v[178:179], v[178:179]
	v_pk_mul_f32 v[224:225], v[180:181], v[180:181]
	v_pk_mul_f32 v[226:227], v[182:183], v[182:183]
	v_pk_mul_f32 v[228:229], v[184:185], v[184:185]
	v_pk_fma_f32 v[222:223], v[222:223], v[234:235], v[232:233]
	v_pk_fma_f32 v[224:225], v[224:225], v[234:235], v[232:233]
	v_pk_fma_f32 v[226:227], v[226:227], v[234:235], v[232:233]
	v_pk_fma_f32 v[228:229], v[228:229], v[234:235], v[232:233]
	v_pk_mul_f32 v[222:223], v[178:179], v[222:223]
	v_pk_mul_f32 v[224:225], v[180:181], v[224:225]
	v_pk_mul_f32 v[226:227], v[182:183], v[226:227]
	v_pk_mul_f32 v[228:229], v[184:185], v[228:229]
	v_exp_f32_e32 v186, v222
	v_exp_f32_e32 v187, v223
	v_exp_f32_e32 v188, v224
	v_exp_f32_e32 v189, v225
	v_exp_f32_e32 v190, v226
	v_exp_f32_e32 v191, v227
	v_exp_f32_e32 v230, v228
	v_exp_f32_e32 v231, v229
	v_pk_add_f32 v[186:187], v[186:187], v[218:219]
	v_pk_add_f32 v[188:189], v[188:189], v[218:219]
	v_pk_add_f32 v[190:191], v[190:191], v[218:219]
	v_pk_add_f32 v[230:231], v[230:231], v[218:219]
	v_rcp_f32_e32 v186, v186
	v_rcp_f32_e32 v187, v187
	v_rcp_f32_e32 v188, v188
	v_rcp_f32_e32 v189, v189
	v_rcp_f32_e32 v190, v190
	v_rcp_f32_e32 v191, v191
	v_rcp_f32_e32 v230, v230
	v_rcp_f32_e32 v231, v231
	v_pk_mul_f32 v[186:187], v[178:179], v[186:187]
	v_pk_mul_f32 v[188:189], v[180:181], v[188:189]
	v_pk_mul_f32 v[190:191], v[182:183], v[190:191]
	v_pk_mul_f32 v[230:231], v[184:185], v[230:231]
	v_pk_mul_f32 v[186:187], v[186:187], v[142:143]
	v_pk_mul_f32 v[188:189], v[188:189], v[144:145]
	v_pk_mul_f32 v[190:191], v[190:191], v[134:135]
	v_pk_mul_f32 v[230:231], v[230:231], v[136:137]
	v_cvt_pk_bf16_f32 v242, v186, v187
	v_cvt_pk_bf16_f32 v243, v188, v189
	v_cvt_pk_bf16_f32 v244, v190, v191
	v_cvt_pk_bf16_f32 v245, v230, v231
	s_cmp_lg_u32 s16, 0
	s_cbranch_scc1 .Lefu_h_all
	s_mov_b64 s[12:13], exec
	s_and_b64 exec, exec, s[48:49]
	v_lshl_or_b32 v0, s40, 1, v200
	s_movk_i32 s17, 0x2c00
	v_mov_b64_e32 v[176:177], s[44:45]
	v_mad_u64_u32 v[176:177], vcc, v0, s17, v[176:177]
	v_lshl_add_u64 v[176:177], v[176:177], 0, v[192:193]
	global_store_dwordx4 v[176:177], v[142:145], off sc1
	s_nop 1
	global_store_dwordx4 v[176:177], v[134:137], off offset:16 sc1
	s_nop 1
	v_mov_b64_e32 v[176:177], s[46:47]
	v_mad_u64_u32 v[176:177], vcc, v0, s17, v[176:177]
	v_lshl_add_u64 v[176:177], v[176:177], 0, v[192:193]
	global_store_dwordx4 v[176:177], v[138:141], off sc1
	s_nop 1
	global_store_dwordx4 v[176:177], v[130:133], off offset:16 sc1
	s_nop 1
	s_andn2_b64 exec, s[12:13], s[48:49]
	global_store_dwordx4 v[238:239], v[242:245], off sc1
	s_nop 1
	s_mov_b64 exec, s[12:13]
	s_branch .Lefu_h_done
.Lefu_h_all:
	global_store_dwordx4 v[238:239], v[242:245], off sc1
	s_nop 1
.Lefu_h_done:
	v_lshl_add_u64 v[238:239], v[238:239], 0, s[14:15]
	ds_read_b32 v176, v197 offset:64
	s_waitcnt lgkmcnt(0)
	v_pk_mul_f32 v[122:123], v[122:123], v[176:177] op_sel_hi:[1,0]
	v_pk_mul_f32 v[124:125], v[124:125], v[176:177] op_sel_hi:[1,0]
	v_pk_mul_f32 v[114:115], v[114:115], v[176:177] op_sel_hi:[1,0]
	v_pk_mul_f32 v[116:117], v[116:117], v[176:177] op_sel_hi:[1,0]
	v_pk_mul_f32 v[126:127], v[126:127], v[176:177] op_sel_hi:[1,0]
	v_pk_mul_f32 v[128:129], v[128:129], v[176:177] op_sel_hi:[1,0]
	v_pk_mul_f32 v[118:119], v[118:119], v[176:177] op_sel_hi:[1,0]
	v_pk_mul_f32 v[120:121], v[120:121], v[176:177] op_sel_hi:[1,0]
	v_cndmask_b32_e64 v202, v122, v138, s[6:7]
	v_cndmask_b32_e64 v203, v123, v139, s[6:7]
	v_cndmask_b32_e64 v204, v124, v140, s[6:7]
	v_cndmask_b32_e64 v205, v125, v141, s[6:7]
	v_cndmask_b32_e64 v206, v114, v130, s[6:7]
	v_cndmask_b32_e64 v207, v115, v131, s[6:7]
	v_cndmask_b32_e64 v208, v116, v132, s[6:7]
	v_cndmask_b32_e64 v209, v117, v133, s[6:7]
	v_cndmask_b32_e64 v210, v122, v138, s[8:9]
	v_cndmask_b32_e64 v211, v123, v139, s[8:9]
	v_cndmask_b32_e64 v212, v124, v140, s[8:9]
	v_cndmask_b32_e64 v213, v125, v141, s[8:9]
	v_cndmask_b32_e64 v214, v114, v130, s[8:9]
	v_cndmask_b32_e64 v215, v115, v131, s[8:9]
	v_cndmask_b32_e64 v216, v116, v132, s[8:9]
	v_cndmask_b32_e64 v217, v117, v133, s[8:9]
	v_pk_fma_f32 v[178:179], v[154:155], v[122:123], v[54:55]
	v_pk_fma_f32 v[180:181], v[156:157], v[124:125], v[56:57]
	v_pk_fma_f32 v[182:183], v[150:151], v[114:115], v[38:39]
	v_pk_fma_f32 v[184:185], v[152:153], v[116:117], v[40:41]
	v_fmac_f32_dpp v178, v202, v158 row_ror:1 row_mask:0xf bank_mask:0xf
	v_fmac_f32_dpp v179, v203, v159 row_ror:1 row_mask:0xf bank_mask:0xf
	v_fmac_f32_dpp v180, v204, v160 row_ror:1 row_mask:0xf bank_mask:0xf
	v_fmac_f32_dpp v181, v205, v161 row_ror:1 row_mask:0xf bank_mask:0xf
	v_fmac_f32_dpp v182, v206, v146 row_ror:1 row_mask:0xf bank_mask:0xf
	v_fmac_f32_dpp v183, v207, v147 row_ror:1 row_mask:0xf bank_mask:0xf
	v_fmac_f32_dpp v184, v208, v148 row_ror:1 row_mask:0xf bank_mask:0xf
	v_fmac_f32_dpp v185, v209, v149 row_ror:1 row_mask:0xf bank_mask:0xf
	v_fmac_f32_dpp v178, v210, v50 row_ror:2 row_mask:0xf bank_mask:0xf
	v_fmac_f32_dpp v179, v211, v51 row_ror:2 row_mask:0xf bank_mask:0xf
	v_fmac_f32_dpp v180, v212, v52 row_ror:2 row_mask:0xf bank_mask:0xf
	v_fmac_f32_dpp v181, v213, v53 row_ror:2 row_mask:0xf bank_mask:0xf
	v_fmac_f32_dpp v182, v214, v34 row_ror:2 row_mask:0xf bank_mask:0xf
	v_fmac_f32_dpp v183, v215, v35 row_ror:2 row_mask:0xf bank_mask:0xf
	v_fmac_f32_dpp v184, v216, v36 row_ror:2 row_mask:0xf bank_mask:0xf
; __device__ __forceinline__ void st16_wt(void* p, u32x4 v) { asm volatile("global_store_dwordx4 %0, %1, off sc1\n\ts_nop 1" :: "v"(p), "v"(v) : "memory"); }
; __device__ __forceinline__ void st16_wt(void* p, f32x4 v) { asm volatile("global_store_dwordx4 %0, %1, off sc1\n\ts_nop 1" :: "v"(p), "v"(v) : "memory"); }
; __device__ __forceinline__ u32x4 pack8(const f32x4& a, const f32x4& b) { u32x4 w; w.x = cvt_pk_bf16(a[0], a[1]); w.y = cvt_pk_bf16(a[2], a[3]); w.z = cvt_pk_bf16(b[0], b[1]); w.w = cvt_pk_bf16(b[2], b[3]); return w; }
;     __device__ __forceinline__ void operator()(const f32x4 (&acc)[2][2][4][2], const Unit& u, int wr, int wc, int fr, int fq) const {
;     ...
;             for (int m = 0; m < 4; ++m) { const int rit = ai * HALF + wr * 64 + m * 16 + fr, row = u.pm * BM + rit; const float r = RST[rit];
;                 f32x4 g[2], vv[2], hv[2];
; #pragma unroll
;                 for (int n = 0; n < 2; ++n) { g[n] = acc[ai][1][m][n] * r; vv[n] = acc[ai][0][m][n] * r;
; #pragma unroll
;                     for (int e = 0; e < 4; ++e) { const float a1 = dpp_mov<0x121>(g[n][e]), a2 = dpp_mov<0x122>(g[n][e]);
;                         const float b1 = m == 0 ? hp1[n][e] : dpp_mov<0x121>(gp[n][e]), b2 = m == 0 ? (fr == 1 ? hp1[n][e] : hp0[n][e]) : dpp_mov<0x122>(gp[n][e]);
;                         const float p1 = fr >= 1 ? a1 : b1, p2 = fr >= 2 ? a2 : b2;
;                         const float cv = bb[n][e] + w0[n][e] * p2 + w1[n][e] * p1 + w2[n][e] * g[n][e];
;                         hv[n][e] = fgelu(cv) * vv[n][e]; } }
;                 if (m == 0 && bnd == 0 && fr < 2) { float* p = fv + ((size_t)u.pm * 2 + fr) * DFF + c0; st16_wt(p, vv[0]); st16_wt(p + 4, vv[1]); float* q = fg + ((size_t)u.pm * 2 + fr) * DFF + c0; st16_wt(q, g[0]); st16_wt(q + 4, g[1]); }
;                 else st16_wt(h + (size_t)row * DFF + c0, pack8(hv[0], hv[1]));
;                 if (m == 3 && bnd == 3 && fr >= 14) { float* p = lg + ((size_t)u.pm * 2 + (fr - 14)) * DFF + c0; st16_wt(p, g[0]); st16_wt(p + 4, g[1]);
;                     if ((u.pm & 7) == 7) { float* q = convout + ((size_t)(u.pm >> 3) * 2 + (fr - 14)) * DFF + c0; *(f32x4*)q = g[0]; *(f32x4*)(q + 4) = g[1]; } }
;                 gp[0] = g[0]; gp[1] = g[1];
;                 asm volatile("" ::: "memory"); }
	v_fmac_f32_dpp v185, v217, v37 row_ror:2 row_mask:0xf bank_mask:0xf
	v_pk_mul_f32 v[222:223], v[178:179], v[178:179]
	v_pk_mul_f32 v[224:225], v[180:181], v[180:181]
	v_pk_mul_f32 v[226:227], v[182:183], v[182:183]
	v_pk_mul_f32 v[228:229], v[184:185], v[184:185]
	v_pk_fma_f32 v[222:223], v[222:223], v[234:235], v[232:233]
	v_pk_fma_f32 v[224:225], v[224:225], v[234:235], v[232:233]
	v_pk_fma_f32 v[226:227], v[226:227], v[234:235], v[232:233]
	v_pk_fma_f32 v[228:229], v[228:229], v[234:235], v[232:233]
	v_pk_mul_f32 v[222:223], v[178:179], v[222:223]
	v_pk_mul_f32 v[224:225], v[180:181], v[224:225]
	v_pk_mul_f32 v[226:227], v[182:183], v[226:227]
	v_pk_mul_f32 v[228:229], v[184:185], v[228:229]
	v_exp_f32_e32 v186, v222
	v_exp_f32_e32 v187, v223
	v_exp_f32_e32 v188, v224
	v_exp_f32_e32 v189, v225
	v_exp_f32_e32 v190, v226
	v_exp_f32_e32 v191, v227
	v_exp_f32_e32 v230, v228
	v_exp_f32_e32 v231, v229
	v_pk_add_f32 v[186:187], v[186:187], v[218:219]
	v_pk_add_f32 v[188:189], v[188:189], v[218:219]
	v_pk_add_f32 v[190:191], v[190:191], v[218:219]
	v_pk_add_f32 v[230:231], v[230:231], v[218:219]
	v_rcp_f32_e32 v186, v186
	v_rcp_f32_e32 v187, v187
	v_rcp_f32_e32 v188, v188
	v_rcp_f32_e32 v189, v189
	v_rcp_f32_e32 v190, v190
	v_rcp_f32_e32 v191, v191
	v_rcp_f32_e32 v230, v230
	v_rcp_f32_e32 v231, v231
	v_pk_mul_f32 v[186:187], v[178:179], v[186:187]
	v_pk_mul_f32 v[188:189], v[180:181], v[188:189]
	v_pk_mul_f32 v[190:191], v[182:183], v[190:191]
	v_pk_mul_f32 v[230:231], v[184:185], v[230:231]
	v_pk_mul_f32 v[186:187], v[186:187], v[126:127]
	v_pk_mul_f32 v[188:189], v[188:189], v[128:129]
	v_pk_mul_f32 v[190:191], v[190:191], v[118:119]
	v_pk_mul_f32 v[230:231], v[230:231], v[120:121]
	v_cvt_pk_bf16_f32 v242, v186, v187
	v_cvt_pk_bf16_f32 v243, v188, v189
	v_cvt_pk_bf16_f32 v244, v190, v191
	v_cvt_pk_bf16_f32 v245, v230, v231
	global_store_dwordx4 v[238:239], v[242:245], off sc1
	s_nop 1
	v_lshl_add_u64 v[238:239], v[238:239], 0, s[14:15]
	ds_read_b32 v176, v197 offset:128
	s_waitcnt lgkmcnt(0)
	v_pk_mul_f32 v[106:107], v[106:107], v[176:177] op_sel_hi:[1,0]
	v_pk_mul_f32 v[108:109], v[108:109], v[176:177] op_sel_hi:[1,0]
	v_pk_mul_f32 v[98:99], v[98:99], v[176:177] op_sel_hi:[1,0]
	v_pk_mul_f32 v[100:101], v[100:101], v[176:177] op_sel_hi:[1,0]
	v_pk_mul_f32 v[110:111], v[110:111], v[176:177] op_sel_hi:[1,0]
	v_pk_mul_f32 v[112:113], v[112:113], v[176:177] op_sel_hi:[1,0]
	v_pk_mul_f32 v[102:103], v[102:103], v[176:177] op_sel_hi:[1,0]
	v_pk_mul_f32 v[104:105], v[104:105], v[176:177] op_sel_hi:[1,0]
	v_cndmask_b32_e64 v202, v106, v122, s[6:7]
	v_cndmask_b32_e64 v203, v107, v123, s[6:7]
	v_cndmask_b32_e64 v204, v108, v124, s[6:7]
	v_cndmask_b32_e64 v205, v109, v125, s[6:7]
	v_cndmask_b32_e64 v206, v98, v114, s[6:7]
	v_cndmask_b32_e64 v207, v99, v115, s[6:7]
	v_cndmask_b32_e64 v208, v100, v116, s[6:7]
	v_cndmask_b32_e64 v209, v101, v117, s[6:7]
	v_cndmask_b32_e64 v210, v106, v122, s[8:9]
	v_cndmask_b32_e64 v211, v107, v123, s[8:9]
	v_cndmask_b32_e64 v212, v108, v124, s[8:9]
	v_cndmask_b32_e64 v213, v109, v125, s[8:9]
	v_cndmask_b32_e64 v214, v98, v114, s[8:9]
	v_cndmask_b32_e64 v215, v99, v115, s[8:9]
	v_cndmask_b32_e64 v216, v100, v116, s[8:9]
	v_cndmask_b32_e64 v217, v101, v117, s[8:9]
	v_pk_fma_f32 v[178:179], v[154:155], v[106:107], v[54:55]
	v_pk_fma_f32 v[180:181], v[156:157], v[108:109], v[56:57]
	v_pk_fma_f32 v[182:183], v[150:151], v[98:99], v[38:39]
	v_pk_fma_f32 v[184:185], v[152:153], v[100:101], v[40:41]
	v_fmac_f32_dpp v178, v202, v158 row_ror:1 row_mask:0xf bank_mask:0xf
	v_fmac_f32_dpp v179, v203, v159 row_ror:1 row_mask:0xf bank_mask:0xf
	v_fmac_f32_dpp v180, v204, v160 row_ror:1 row_mask:0xf bank_mask:0xf
	v_fmac_f32_dpp v181, v205, v161 row_ror:1 row_mask:0xf bank_mask:0xf
	v_fmac_f32_dpp v182, v206, v146 row_ror:1 row_mask:0xf bank_mask:0xf
	v_fmac_f32_dpp v183, v207, v147 row_ror:1 row_mask:0xf bank_mask:0xf
	v_fmac_f32_dpp v184, v208, v148 row_ror:1 row_mask:0xf bank_mask:0xf
	v_fmac_f32_dpp v185, v209, v149 row_ror:1 row_mask:0xf bank_mask:0xf
	v_fmac_f32_dpp v178, v210, v50 row_ror:2 row_mask:0xf bank_mask:0xf
	v_fmac_f32_dpp v179, v211, v51 row_ror:2 row_mask:0xf bank_mask:0xf
	v_fmac_f32_dpp v180, v212, v52 row_ror:2 row_mask:0xf bank_mask:0xf
	v_fmac_f32_dpp v181, v213, v53 row_ror:2 row_mask:0xf bank_mask:0xf
	v_fmac_f32_dpp v182, v214, v34 row_ror:2 row_mask:0xf bank_mask:0xf
	v_fmac_f32_dpp v183, v215, v35 row_ror:2 row_mask:0xf bank_mask:0xf
	v_fmac_f32_dpp v184, v216, v36 row_ror:2 row_mask:0xf bank_mask:0xf
	v_fmac_f32_dpp v185, v217, v37 row_ror:2 row_mask:0xf bank_mask:0xf
	v_pk_mul_f32 v[222:223], v[178:179], v[178:179]
	v_pk_mul_f32 v[224:225], v[180:181], v[180:181]
	v_pk_mul_f32 v[226:227], v[182:183], v[182:183]
	v_pk_mul_f32 v[228:229], v[184:185], v[184:185]
	v_pk_fma_f32 v[222:223], v[222:223], v[234:235], v[232:233]
	v_pk_fma_f32 v[224:225], v[224:225], v[234:235], v[232:233]
	v_pk_fma_f32 v[226:227], v[226:227], v[234:235], v[232:233]
	v_pk_fma_f32 v[228:229], v[228:229], v[234:235], v[232:233]
	v_pk_mul_f32 v[222:223], v[178:179], v[222:223]
	v_pk_mul_f32 v[224:225], v[180:181], v[224:225]
	v_pk_mul_f32 v[226:227], v[182:183], v[226:227]
	v_pk_mul_f32 v[228:229], v[184:185], v[228:229]
	v_exp_f32_e32 v186, v222
	v_exp_f32_e32 v187, v223
	v_exp_f32_e32 v188, v224
	v_exp_f32_e32 v189, v225
	v_exp_f32_e32 v190, v226
	v_exp_f32_e32 v191, v227
	v_exp_f32_e32 v230, v228
	v_exp_f32_e32 v231, v229
	v_pk_add_f32 v[186:187], v[186:187], v[218:219]
	v_pk_add_f32 v[188:189], v[188:189], v[218:219]
	v_pk_add_f32 v[190:191], v[190:191], v[218:219]
	v_pk_add_f32 v[230:231], v[230:231], v[218:219]
	v_rcp_f32_e32 v186, v186
	v_rcp_f32_e32 v187, v187
	v_rcp_f32_e32 v188, v188
	v_rcp_f32_e32 v189, v189
	v_rcp_f32_e32 v190, v190
	v_rcp_f32_e32 v191, v191
	v_rcp_f32_e32 v230, v230
	v_rcp_f32_e32 v231, v231
	v_pk_mul_f32 v[186:187], v[178:179], v[186:187]
	v_pk_mul_f32 v[188:189], v[180:181], v[188:189]
	v_pk_mul_f32 v[190:191], v[182:183], v[190:191]
	v_pk_mul_f32 v[230:231], v[184:185], v[230:231]
	v_pk_mul_f32 v[186:187], v[186:187], v[110:111]
	v_pk_mul_f32 v[188:189], v[188:189], v[112:113]
	v_pk_mul_f32 v[190:191], v[190:191], v[102:103]
	v_pk_mul_f32 v[230:231], v[230:231], v[104:105]
	v_cvt_pk_bf16_f32 v242, v186, v187
	v_cvt_pk_bf16_f32 v243, v188, v189
	v_cvt_pk_bf16_f32 v244, v190, v191
	v_cvt_pk_bf16_f32 v245, v230, v231
	global_store_dwordx4 v[238:239], v[242:245], off sc1
	s_nop 1
	v_lshl_add_u64 v[238:239], v[238:239], 0, s[14:15]
	ds_read_b32 v176, v197 offset:192
	s_waitcnt lgkmcnt(0)
; #define PG8_LAS __attribute__((address_space(3)))
; template <int CTRL> __device__ __forceinline__ float dpp_mov(float x) { return __builtin_bit_cast(float, __builtin_amdgcn_update_dpp(0, __builtin_bit_cast(int, x), CTRL, 0xf, 0xf, false)); }
;     __device__ __forceinline__ void operator()(const f32x4 (&acc)[2][2][4][2], const Unit& u, int wr, int wc, int fr, int fq) const {
;     ...
;         for (int ai = 0; ai < 2; ++ai) { const int bnd = 2 * ai + wr;
;             f32x4 hp0[2], hp1[2], gp[2];
;             { const int pb_ = bnd > 0 ? bnd - 1 : 0; const float r0 = bnd > 0 ? RST[64 * bnd - 2] : 0.f, r1 = bnd > 0 ? RST[64 * bnd - 1] : 0.f;
; #pragma unroll
;               for (int n = 0; n < 2; ++n) { hp0[n] = *(const PG8_LAS f32x4*)(xch + (pb_ * 2 + 0) * 128 + cb + 4 * n) * r0; hp1[n] = *(const PG8_LAS f32x4*)(xch + (pb_ * 2 + 1) * 128 + cb + 4 * n) * r1; gp[n] = hp0[n]; } }
; #pragma unroll
;             for (int m = 0; m < 4; ++m) { const int rit = ai * HALF + wr * 64 + m * 16 + fr, row = u.pm * BM + rit; const float r = RST[rit];
;                 f32x4 g[2], vv[2], hv[2];
; #pragma unroll
;                 for (int n = 0; n < 2; ++n) { g[n] = acc[ai][1][m][n] * r; vv[n] = acc[ai][0][m][n] * r;
; #pragma unroll
;                     for (int e = 0; e < 4; ++e) { const float a1 = dpp_mov<0x121>(g[n][e]), a2 = dpp_mov<0x122>(g[n][e]);
;                         const float b1 = m == 0 ? hp1[n][e] : dpp_mov<0x121>(gp[n][e]), b2 = m == 0 ? (fr == 1 ? hp1[n][e] : hp0[n][e]) : dpp_mov<0x122>(gp[n][e]);
;                         const float p1 = fr >= 1 ? a1 : b1, p2 = fr >= 2 ? a2 : b2;
;                         const float cv = bb[n][e] + w0[n][e] * p2 + w1[n][e] * p1 + w2[n][e] * g[n][e];
;                         hv[n][e] = fgelu(cv) * vv[n][e]; } }
	v_pk_mul_f32 v[90:91], v[90:91], v[176:177] op_sel_hi:[1,0]
	v_pk_mul_f32 v[92:93], v[92:93], v[176:177] op_sel_hi:[1,0]
	v_pk_mul_f32 v[82:83], v[82:83], v[176:177] op_sel_hi:[1,0]
	v_pk_mul_f32 v[84:85], v[84:85], v[176:177] op_sel_hi:[1,0]
	v_pk_mul_f32 v[94:95], v[94:95], v[176:177] op_sel_hi:[1,0]
	v_pk_mul_f32 v[96:97], v[96:97], v[176:177] op_sel_hi:[1,0]
	v_pk_mul_f32 v[86:87], v[86:87], v[176:177] op_sel_hi:[1,0]
	v_pk_mul_f32 v[88:89], v[88:89], v[176:177] op_sel_hi:[1,0]
	v_cndmask_b32_e64 v202, v90, v106, s[6:7]
	v_cndmask_b32_e64 v203, v91, v107, s[6:7]
	v_cndmask_b32_e64 v204, v92, v108, s[6:7]
	v_cndmask_b32_e64 v205, v93, v109, s[6:7]
	v_cndmask_b32_e64 v206, v82, v98, s[6:7]
	v_cndmask_b32_e64 v207, v83, v99, s[6:7]
	v_cndmask_b32_e64 v208, v84, v100, s[6:7]
	v_cndmask_b32_e64 v209, v85, v101, s[6:7]
	v_cndmask_b32_e64 v210, v90, v106, s[8:9]
	v_cndmask_b32_e64 v211, v91, v107, s[8:9]
	v_cndmask_b32_e64 v212, v92, v108, s[8:9]
	v_cndmask_b32_e64 v213, v93, v109, s[8:9]
	v_cndmask_b32_e64 v214, v82, v98, s[8:9]
	v_cndmask_b32_e64 v215, v83, v99, s[8:9]
	v_cndmask_b32_e64 v216, v84, v100, s[8:9]
	v_cndmask_b32_e64 v217, v85, v101, s[8:9]
	v_pk_fma_f32 v[178:179], v[154:155], v[90:91], v[54:55]
	v_pk_fma_f32 v[180:181], v[156:157], v[92:93], v[56:57]
	v_pk_fma_f32 v[182:183], v[150:151], v[82:83], v[38:39]
	v_pk_fma_f32 v[184:185], v[152:153], v[84:85], v[40:41]
	v_fmac_f32_dpp v178, v202, v158 row_ror:1 row_mask:0xf bank_mask:0xf
	v_fmac_f32_dpp v179, v203, v159 row_ror:1 row_mask:0xf bank_mask:0xf
	v_fmac_f32_dpp v180, v204, v160 row_ror:1 row_mask:0xf bank_mask:0xf
	v_fmac_f32_dpp v181, v205, v161 row_ror:1 row_mask:0xf bank_mask:0xf
	v_fmac_f32_dpp v182, v206, v146 row_ror:1 row_mask:0xf bank_mask:0xf
	v_fmac_f32_dpp v183, v207, v147 row_ror:1 row_mask:0xf bank_mask:0xf
	v_fmac_f32_dpp v184, v208, v148 row_ror:1 row_mask:0xf bank_mask:0xf
	v_fmac_f32_dpp v185, v209, v149 row_ror:1 row_mask:0xf bank_mask:0xf
	v_fmac_f32_dpp v178, v210, v50 row_ror:2 row_mask:0xf bank_mask:0xf
	v_fmac_f32_dpp v179, v211, v51 row_ror:2 row_mask:0xf bank_mask:0xf
	v_fmac_f32_dpp v180, v212, v52 row_ror:2 row_mask:0xf bank_mask:0xf
	v_fmac_f32_dpp v181, v213, v53 row_ror:2 row_mask:0xf bank_mask:0xf
	v_fmac_f32_dpp v182, v214, v34 row_ror:2 row_mask:0xf bank_mask:0xf
	v_fmac_f32_dpp v183, v215, v35 row_ror:2 row_mask:0xf bank_mask:0xf
	v_fmac_f32_dpp v184, v216, v36 row_ror:2 row_mask:0xf bank_mask:0xf
	v_fmac_f32_dpp v185, v217, v37 row_ror:2 row_mask:0xf bank_mask:0xf
	v_pk_mul_f32 v[222:223], v[178:179], v[178:179]
	v_pk_mul_f32 v[224:225], v[180:181], v[180:181]
	v_pk_mul_f32 v[226:227], v[182:183], v[182:183]
	v_pk_mul_f32 v[228:229], v[184:185], v[184:185]
	v_pk_fma_f32 v[222:223], v[222:223], v[234:235], v[232:233]
	v_pk_fma_f32 v[224:225], v[224:225], v[234:235], v[232:233]
	v_pk_fma_f32 v[226:227], v[226:227], v[234:235], v[232:233]
	v_pk_fma_f32 v[228:229], v[228:229], v[234:235], v[232:233]
	v_pk_mul_f32 v[222:223], v[178:179], v[222:223]
	v_pk_mul_f32 v[224:225], v[180:181], v[224:225]
	v_pk_mul_f32 v[226:227], v[182:183], v[226:227]
	v_pk_mul_f32 v[228:229], v[184:185], v[228:229]
	v_exp_f32_e32 v186, v222
	v_exp_f32_e32 v187, v223
	v_exp_f32_e32 v188, v224
	v_exp_f32_e32 v189, v225
	v_exp_f32_e32 v190, v226
	v_exp_f32_e32 v191, v227
	v_exp_f32_e32 v230, v228
	v_exp_f32_e32 v231, v229
	v_pk_add_f32 v[186:187], v[186:187], v[218:219]
	v_pk_add_f32 v[188:189], v[188:189], v[218:219]
	v_pk_add_f32 v[190:191], v[190:191], v[218:219]
	v_pk_add_f32 v[230:231], v[230:231], v[218:219]
	v_rcp_f32_e32 v186, v186
	v_rcp_f32_e32 v187, v187
	v_rcp_f32_e32 v188, v188
	v_rcp_f32_e32 v189, v189
	v_rcp_f32_e32 v190, v190
	v_rcp_f32_e32 v191, v191
	v_rcp_f32_e32 v230, v230
	v_rcp_f32_e32 v231, v231
	v_pk_mul_f32 v[186:187], v[178:179], v[186:187]
	v_pk_mul_f32 v[188:189], v[180:181], v[188:189]
	v_pk_mul_f32 v[190:191], v[182:183], v[190:191]
	v_pk_mul_f32 v[230:231], v[184:185], v[230:231]
	v_pk_mul_f32 v[186:187], v[186:187], v[94:95]
	v_pk_mul_f32 v[188:189], v[188:189], v[96:97]
	v_pk_mul_f32 v[190:191], v[190:191], v[86:87]
	v_pk_mul_f32 v[230:231], v[230:231], v[88:89]
	v_cvt_pk_bf16_f32 v242, v186, v187
	v_cvt_pk_bf16_f32 v243, v188, v189
	v_cvt_pk_bf16_f32 v244, v190, v191
	v_cvt_pk_bf16_f32 v245, v230, v231
	global_store_dwordx4 v[238:239], v[242:245], off sc1
	s_nop 1
	s_mov_b32 s14, 0x6e000
	v_lshl_add_u64 v[238:239], v[238:239], 0, s[14:15]
	s_mov_b32 s14, 0x16000
	s_lshl_b32 s17, s16, 4
	s_add_i32 s17, s17, s34
	s_add_i32 s17, s17, -3072
	v_add_u32_e32 v198, s17, v199
	s_lshl_b32 s17, s16, 2
	s_add_i32 s17, s17, s34
	s_add_i32 s17, s17, 504
	v_mov_b32_e32 v0, s17
	ds_read_b128 v[210:213], v198
	ds_read_b128 v[214:217], v198 offset:16
	ds_read_b128 v[202:205], v198 offset:512
	ds_read_b128 v[206:209], v198 offset:528
	ds_read_b64 v[176:177], v0
	s_waitcnt lgkmcnt(0)
	v_pk_mul_f32 v[210:211], v[210:211], v[176:177] op_sel_hi:[1,0]
	v_pk_mul_f32 v[212:213], v[212:213], v[176:177] op_sel_hi:[1,0]
	v_pk_mul_f32 v[214:215], v[214:215], v[176:177] op_sel_hi:[1,0]
	v_pk_mul_f32 v[216:217], v[216:217], v[176:177] op_sel_hi:[1,0]
	v_mul_f32_e32 v202, v177, v202
	v_mul_f32_e32 v203, v177, v203
	v_mul_f32_e32 v204, v177, v204
	v_mul_f32_e32 v205, v177, v205
	v_mul_f32_e32 v206, v177, v206
	v_mul_f32_e32 v207, v177, v207
	v_mul_f32_e32 v208, v177, v208
	v_mul_f32_e32 v209, v177, v209
	v_cndmask_b32_e64 v210, v202, v210, s[10:11]
	v_cndmask_b32_e64 v211, v203, v211, s[10:11]
	v_cndmask_b32_e64 v212, v204, v212, s[10:11]
	v_cndmask_b32_e64 v213, v205, v213, s[10:11]
	v_cndmask_b32_e64 v214, v206, v214, s[10:11]
	v_cndmask_b32_e64 v215, v207, v215, s[10:11]
	v_cndmask_b32_e64 v216, v208, v216, s[10:11]
	v_cndmask_b32_e64 v217, v209, v217, s[10:11]
	ds_read_b32 v176, v197 offset:512
	s_waitcnt lgkmcnt(0)
; __device__ __forceinline__ void st16_wt(void* p, u32x4 v) { asm volatile("global_store_dwordx4 %0, %1, off sc1\n\ts_nop 1" :: "v"(p), "v"(v) : "memory"); }
; __device__ __forceinline__ void st16_wt(void* p, f32x4 v) { asm volatile("global_store_dwordx4 %0, %1, off sc1\n\ts_nop 1" :: "v"(p), "v"(v) : "memory"); }
; __device__ __forceinline__ u32x4 pack8(const f32x4& a, const f32x4& b) { u32x4 w; w.x = cvt_pk_bf16(a[0], a[1]); w.y = cvt_pk_bf16(a[2], a[3]); w.z = cvt_pk_bf16(b[0], b[1]); w.w = cvt_pk_bf16(b[2], b[3]); return w; }
;     __device__ __forceinline__ void operator()(const f32x4 (&acc)[2][2][4][2], const Unit& u, int wr, int wc, int fr, int fq) const {
;     ...
;             for (int m = 0; m < 4; ++m) { const int rit = ai * HALF + wr * 64 + m * 16 + fr, row = u.pm * BM + rit; const float r = RST[rit];
;                 f32x4 g[2], vv[2], hv[2];
; #pragma unroll
;                 for (int n = 0; n < 2; ++n) { g[n] = acc[ai][1][m][n] * r; vv[n] = acc[ai][0][m][n] * r;
; #pragma unroll
;                     for (int e = 0; e < 4; ++e) { const float a1 = dpp_mov<0x121>(g[n][e]), a2 = dpp_mov<0x122>(g[n][e]);
;                         const float b1 = m == 0 ? hp1[n][e] : dpp_mov<0x121>(gp[n][e]), b2 = m == 0 ? (fr == 1 ? hp1[n][e] : hp0[n][e]) : dpp_mov<0x122>(gp[n][e]);
;                         const float p1 = fr >= 1 ? a1 : b1, p2 = fr >= 2 ? a2 : b2;
;                         const float cv = bb[n][e] + w0[n][e] * p2 + w1[n][e] * p1 + w2[n][e] * g[n][e];
;                         hv[n][e] = fgelu(cv) * vv[n][e]; } }
;                 if (m == 0 && bnd == 0 && fr < 2) { float* p = fv + ((size_t)u.pm * 2 + fr) * DFF + c0; st16_wt(p, vv[0]); st16_wt(p + 4, vv[1]); float* q = fg + ((size_t)u.pm * 2 + fr) * DFF + c0; st16_wt(q, g[0]); st16_wt(q + 4, g[1]); }
;                 else st16_wt(h + (size_t)row * DFF + c0, pack8(hv[0], hv[1]));
;                 if (m == 3 && bnd == 3 && fr >= 14) { float* p = lg + ((size_t)u.pm * 2 + (fr - 14)) * DFF + c0; st16_wt(p, g[0]); st16_wt(p + 4, g[1]);
;                     if ((u.pm & 7) == 7) { float* q = convout + ((size_t)(u.pm >> 3) * 2 + (fr - 14)) * DFF + c0; *(f32x4*)q = g[0]; *(f32x4*)(q + 4) = g[1]; } }
;                 gp[0] = g[0]; gp[1] = g[1];
;                 asm volatile("" ::: "memory"); }
	v_pk_mul_f32 v[74:75], v[74:75], v[176:177] op_sel_hi:[1,0]
	v_pk_mul_f32 v[76:77], v[76:77], v[176:177] op_sel_hi:[1,0]
	v_pk_mul_f32 v[66:67], v[66:67], v[176:177] op_sel_hi:[1,0]
	v_pk_mul_f32 v[68:69], v[68:69], v[176:177] op_sel_hi:[1,0]
	v_pk_mul_f32 v[78:79], v[78:79], v[176:177] op_sel_hi:[1,0]
	v_pk_mul_f32 v[80:81], v[80:81], v[176:177] op_sel_hi:[1,0]
	v_pk_mul_f32 v[70:71], v[70:71], v[176:177] op_sel_hi:[1,0]
	v_pk_mul_f32 v[72:73], v[72:73], v[176:177] op_sel_hi:[1,0]
	v_cndmask_b32_e64 v202, v74, v202, s[6:7]
	v_cndmask_b32_e64 v203, v75, v203, s[6:7]
	v_cndmask_b32_e64 v204, v76, v204, s[6:7]
	v_cndmask_b32_e64 v205, v77, v205, s[6:7]
	v_cndmask_b32_e64 v206, v66, v206, s[6:7]
	v_cndmask_b32_e64 v207, v67, v207, s[6:7]
	v_cndmask_b32_e64 v208, v68, v208, s[6:7]
	v_cndmask_b32_e64 v209, v69, v209, s[6:7]
	v_cndmask_b32_e64 v210, v74, v210, s[8:9]
	v_cndmask_b32_e64 v211, v75, v211, s[8:9]
	v_cndmask_b32_e64 v212, v76, v212, s[8:9]
	v_cndmask_b32_e64 v213, v77, v213, s[8:9]
	v_cndmask_b32_e64 v214, v66, v214, s[8:9]
	v_cndmask_b32_e64 v215, v67, v215, s[8:9]
	v_cndmask_b32_e64 v216, v68, v216, s[8:9]
	v_cndmask_b32_e64 v217, v69, v217, s[8:9]
	v_pk_fma_f32 v[178:179], v[154:155], v[74:75], v[54:55]
	v_pk_fma_f32 v[180:181], v[156:157], v[76:77], v[56:57]
	v_pk_fma_f32 v[182:183], v[150:151], v[66:67], v[38:39]
	v_pk_fma_f32 v[184:185], v[152:153], v[68:69], v[40:41]
	v_fmac_f32_dpp v178, v202, v158 row_ror:1 row_mask:0xf bank_mask:0xf
	v_fmac_f32_dpp v179, v203, v159 row_ror:1 row_mask:0xf bank_mask:0xf
	v_fmac_f32_dpp v180, v204, v160 row_ror:1 row_mask:0xf bank_mask:0xf
	v_fmac_f32_dpp v181, v205, v161 row_ror:1 row_mask:0xf bank_mask:0xf
	v_fmac_f32_dpp v182, v206, v146 row_ror:1 row_mask:0xf bank_mask:0xf
	v_fmac_f32_dpp v183, v207, v147 row_ror:1 row_mask:0xf bank_mask:0xf
	v_fmac_f32_dpp v184, v208, v148 row_ror:1 row_mask:0xf bank_mask:0xf
	v_fmac_f32_dpp v185, v209, v149 row_ror:1 row_mask:0xf bank_mask:0xf
	v_fmac_f32_dpp v178, v210, v50 row_ror:2 row_mask:0xf bank_mask:0xf
	v_fmac_f32_dpp v179, v211, v51 row_ror:2 row_mask:0xf bank_mask:0xf
	v_fmac_f32_dpp v180, v212, v52 row_ror:2 row_mask:0xf bank_mask:0xf
	v_fmac_f32_dpp v181, v213, v53 row_ror:2 row_mask:0xf bank_mask:0xf
	v_fmac_f32_dpp v182, v214, v34 row_ror:2 row_mask:0xf bank_mask:0xf
	v_fmac_f32_dpp v183, v215, v35 row_ror:2 row_mask:0xf bank_mask:0xf
	v_fmac_f32_dpp v184, v216, v36 row_ror:2 row_mask:0xf bank_mask:0xf
	v_fmac_f32_dpp v185, v217, v37 row_ror:2 row_mask:0xf bank_mask:0xf
	v_pk_mul_f32 v[222:223], v[178:179], v[178:179]
	v_pk_mul_f32 v[224:225], v[180:181], v[180:181]
	v_pk_mul_f32 v[226:227], v[182:183], v[182:183]
	v_pk_mul_f32 v[228:229], v[184:185], v[184:185]
	v_pk_fma_f32 v[222:223], v[222:223], v[234:235], v[232:233]
	v_pk_fma_f32 v[224:225], v[224:225], v[234:235], v[232:233]
	v_pk_fma_f32 v[226:227], v[226:227], v[234:235], v[232:233]
	v_pk_fma_f32 v[228:229], v[228:229], v[234:235], v[232:233]
	v_pk_mul_f32 v[222:223], v[178:179], v[222:223]
	v_pk_mul_f32 v[224:225], v[180:181], v[224:225]
	v_pk_mul_f32 v[226:227], v[182:183], v[226:227]
	v_pk_mul_f32 v[228:229], v[184:185], v[228:229]
	v_exp_f32_e32 v186, v222
	v_exp_f32_e32 v187, v223
	v_exp_f32_e32 v188, v224
	v_exp_f32_e32 v189, v225
	v_exp_f32_e32 v190, v226
	v_exp_f32_e32 v191, v227
	v_exp_f32_e32 v230, v228
	v_exp_f32_e32 v231, v229
	v_pk_add_f32 v[186:187], v[186:187], v[218:219]
	v_pk_add_f32 v[188:189], v[188:189], v[218:219]
	v_pk_add_f32 v[190:191], v[190:191], v[218:219]
	v_pk_add_f32 v[230:231], v[230:231], v[218:219]
	v_rcp_f32_e32 v186, v186
	v_rcp_f32_e32 v187, v187
	v_rcp_f32_e32 v188, v188
	v_rcp_f32_e32 v189, v189
	v_rcp_f32_e32 v190, v190
	v_rcp_f32_e32 v191, v191
	v_rcp_f32_e32 v230, v230
	v_rcp_f32_e32 v231, v231
	v_pk_mul_f32 v[186:187], v[178:179], v[186:187]
	v_pk_mul_f32 v[188:189], v[180:181], v[188:189]
	v_pk_mul_f32 v[190:191], v[182:183], v[190:191]
	v_pk_mul_f32 v[230:231], v[184:185], v[230:231]
	v_pk_mul_f32 v[186:187], v[186:187], v[78:79]
	v_pk_mul_f32 v[188:189], v[188:189], v[80:81]
	v_pk_mul_f32 v[190:191], v[190:191], v[70:71]
	v_pk_mul_f32 v[230:231], v[230:231], v[72:73]
	v_cvt_pk_bf16_f32 v242, v186, v187
	v_cvt_pk_bf16_f32 v243, v188, v189
	v_cvt_pk_bf16_f32 v244, v190, v191
	v_cvt_pk_bf16_f32 v245, v230, v231
	global_store_dwordx4 v[238:239], v[242:245], off sc1
	s_nop 1
	v_lshl_add_u64 v[238:239], v[238:239], 0, s[14:15]
	ds_read_b32 v176, v197 offset:576
	s_waitcnt lgkmcnt(0)
; __device__ __forceinline__ void st16_wt(void* p, u32x4 v) { asm volatile("global_store_dwordx4 %0, %1, off sc1\n\ts_nop 1" :: "v"(p), "v"(v) : "memory"); }
; __device__ __forceinline__ void st16_wt(void* p, f32x4 v) { asm volatile("global_store_dwordx4 %0, %1, off sc1\n\ts_nop 1" :: "v"(p), "v"(v) : "memory"); }
; __device__ __forceinline__ u32x4 pack8(const f32x4& a, const f32x4& b) { u32x4 w; w.x = cvt_pk_bf16(a[0], a[1]); w.y = cvt_pk_bf16(a[2], a[3]); w.z = cvt_pk_bf16(b[0], b[1]); w.w = cvt_pk_bf16(b[2], b[3]); return w; }
;     __device__ __forceinline__ void operator()(const f32x4 (&acc)[2][2][4][2], const Unit& u, int wr, int wc, int fr, int fq) const {
;     ...
;             for (int m = 0; m < 4; ++m) { const int rit = ai * HALF + wr * 64 + m * 16 + fr, row = u.pm * BM + rit; const float r = RST[rit];
;                 f32x4 g[2], vv[2], hv[2];
; #pragma unroll
;                 for (int n = 0; n < 2; ++n) { g[n] = acc[ai][1][m][n] * r; vv[n] = acc[ai][0][m][n] * r;
; #pragma unroll
;                     for (int e = 0; e < 4; ++e) { const float a1 = dpp_mov<0x121>(g[n][e]), a2 = dpp_mov<0x122>(g[n][e]);
;                         const float b1 = m == 0 ? hp1[n][e] : dpp_mov<0x121>(gp[n][e]), b2 = m == 0 ? (fr == 1 ? hp1[n][e] : hp0[n][e]) : dpp_mov<0x122>(gp[n][e]);
;                         const float p1 = fr >= 1 ? a1 : b1, p2 = fr >= 2 ? a2 : b2;
;                         const float cv = bb[n][e] + w0[n][e] * p2 + w1[n][e] * p1 + w2[n][e] * g[n][e];
;                         hv[n][e] = fgelu(cv) * vv[n][e]; } }
;                 if (m == 0 && bnd == 0 && fr < 2) { float* p = fv + ((size_t)u.pm * 2 + fr) * DFF + c0; st16_wt(p, vv[0]); st16_wt(p + 4, vv[1]); float* q = fg + ((size_t)u.pm * 2 + fr) * DFF + c0; st16_wt(q, g[0]); st16_wt(q + 4, g[1]); }
;                 else st16_wt(h + (size_t)row * DFF + c0, pack8(hv[0], hv[1]));
;                 if (m == 3 && bnd == 3 && fr >= 14) { float* p = lg + ((size_t)u.pm * 2 + (fr - 14)) * DFF + c0; st16_wt(p, g[0]); st16_wt(p + 4, g[1]);
;                     if ((u.pm & 7) == 7) { float* q = convout + ((size_t)(u.pm >> 3) * 2 + (fr - 14)) * DFF + c0; *(f32x4*)q = g[0]; *(f32x4*)(q + 4) = g[1]; } }
;                 gp[0] = g[0]; gp[1] = g[1];
;                 asm volatile("" ::: "memory"); }
	v_pk_mul_f32 v[58:59], v[58:59], v[176:177] op_sel_hi:[1,0]
	v_pk_mul_f32 v[60:61], v[60:61], v[176:177] op_sel_hi:[1,0]
	v_pk_mul_f32 v[42:43], v[42:43], v[176:177] op_sel_hi:[1,0]
	v_pk_mul_f32 v[44:45], v[44:45], v[176:177] op_sel_hi:[1,0]
	v_pk_mul_f32 v[62:63], v[62:63], v[176:177] op_sel_hi:[1,0]
	v_pk_mul_f32 v[64:65], v[64:65], v[176:177] op_sel_hi:[1,0]
	v_pk_mul_f32 v[46:47], v[46:47], v[176:177] op_sel_hi:[1,0]
	v_pk_mul_f32 v[48:49], v[48:49], v[176:177] op_sel_hi:[1,0]
	v_cndmask_b32_e64 v202, v58, v74, s[6:7]
	v_cndmask_b32_e64 v203, v59, v75, s[6:7]
	v_cndmask_b32_e64 v204, v60, v76, s[6:7]
	v_cndmask_b32_e64 v205, v61, v77, s[6:7]
	v_cndmask_b32_e64 v206, v42, v66, s[6:7]
	v_cndmask_b32_e64 v207, v43, v67, s[6:7]
	v_cndmask_b32_e64 v208, v44, v68, s[6:7]
	v_cndmask_b32_e64 v209, v45, v69, s[6:7]
	v_cndmask_b32_e64 v210, v58, v74, s[8:9]
	v_cndmask_b32_e64 v211, v59, v75, s[8:9]
	v_cndmask_b32_e64 v212, v60, v76, s[8:9]
	v_cndmask_b32_e64 v213, v61, v77, s[8:9]
	v_cndmask_b32_e64 v214, v42, v66, s[8:9]
	v_cndmask_b32_e64 v215, v43, v67, s[8:9]
	v_cndmask_b32_e64 v216, v44, v68, s[8:9]
	v_cndmask_b32_e64 v217, v45, v69, s[8:9]
	v_pk_fma_f32 v[178:179], v[154:155], v[58:59], v[54:55]
	v_pk_fma_f32 v[180:181], v[156:157], v[60:61], v[56:57]
	v_pk_fma_f32 v[182:183], v[150:151], v[42:43], v[38:39]
	v_pk_fma_f32 v[184:185], v[152:153], v[44:45], v[40:41]
	v_fmac_f32_dpp v178, v202, v158 row_ror:1 row_mask:0xf bank_mask:0xf
	v_fmac_f32_dpp v179, v203, v159 row_ror:1 row_mask:0xf bank_mask:0xf
	v_fmac_f32_dpp v180, v204, v160 row_ror:1 row_mask:0xf bank_mask:0xf
	v_fmac_f32_dpp v181, v205, v161 row_ror:1 row_mask:0xf bank_mask:0xf
	v_fmac_f32_dpp v182, v206, v146 row_ror:1 row_mask:0xf bank_mask:0xf
	v_fmac_f32_dpp v183, v207, v147 row_ror:1 row_mask:0xf bank_mask:0xf
	v_fmac_f32_dpp v184, v208, v148 row_ror:1 row_mask:0xf bank_mask:0xf
	v_fmac_f32_dpp v185, v209, v149 row_ror:1 row_mask:0xf bank_mask:0xf
	v_fmac_f32_dpp v178, v210, v50 row_ror:2 row_mask:0xf bank_mask:0xf
	v_fmac_f32_dpp v179, v211, v51 row_ror:2 row_mask:0xf bank_mask:0xf
	v_fmac_f32_dpp v180, v212, v52 row_ror:2 row_mask:0xf bank_mask:0xf
	v_fmac_f32_dpp v181, v213, v53 row_ror:2 row_mask:0xf bank_mask:0xf
	v_fmac_f32_dpp v182, v214, v34 row_ror:2 row_mask:0xf bank_mask:0xf
	v_fmac_f32_dpp v183, v215, v35 row_ror:2 row_mask:0xf bank_mask:0xf
	v_fmac_f32_dpp v184, v216, v36 row_ror:2 row_mask:0xf bank_mask:0xf
	v_fmac_f32_dpp v185, v217, v37 row_ror:2 row_mask:0xf bank_mask:0xf
	v_pk_mul_f32 v[222:223], v[178:179], v[178:179]
	v_pk_mul_f32 v[224:225], v[180:181], v[180:181]
	v_pk_mul_f32 v[226:227], v[182:183], v[182:183]
	v_pk_mul_f32 v[228:229], v[184:185], v[184:185]
	v_pk_fma_f32 v[222:223], v[222:223], v[234:235], v[232:233]
	v_pk_fma_f32 v[224:225], v[224:225], v[234:235], v[232:233]
	v_pk_fma_f32 v[226:227], v[226:227], v[234:235], v[232:233]
	v_pk_fma_f32 v[228:229], v[228:229], v[234:235], v[232:233]
	v_pk_mul_f32 v[222:223], v[178:179], v[222:223]
	v_pk_mul_f32 v[224:225], v[180:181], v[224:225]
	v_pk_mul_f32 v[226:227], v[182:183], v[226:227]
	v_pk_mul_f32 v[228:229], v[184:185], v[228:229]
	v_exp_f32_e32 v186, v222
	v_exp_f32_e32 v187, v223
	v_exp_f32_e32 v188, v224
	v_exp_f32_e32 v189, v225
	v_exp_f32_e32 v190, v226
	v_exp_f32_e32 v191, v227
	v_exp_f32_e32 v230, v228
	v_exp_f32_e32 v231, v229
	v_pk_add_f32 v[186:187], v[186:187], v[218:219]
	v_pk_add_f32 v[188:189], v[188:189], v[218:219]
	v_pk_add_f32 v[190:191], v[190:191], v[218:219]
	v_pk_add_f32 v[230:231], v[230:231], v[218:219]
	v_rcp_f32_e32 v186, v186
	v_rcp_f32_e32 v187, v187
	v_rcp_f32_e32 v188, v188
	v_rcp_f32_e32 v189, v189
	v_rcp_f32_e32 v190, v190
	v_rcp_f32_e32 v191, v191
	v_rcp_f32_e32 v230, v230
	v_rcp_f32_e32 v231, v231
	v_pk_mul_f32 v[186:187], v[178:179], v[186:187]
	v_pk_mul_f32 v[188:189], v[180:181], v[188:189]
	v_pk_mul_f32 v[190:191], v[182:183], v[190:191]
	v_pk_mul_f32 v[230:231], v[184:185], v[230:231]
	v_pk_mul_f32 v[186:187], v[186:187], v[62:63]
	v_pk_mul_f32 v[188:189], v[188:189], v[64:65]
	v_pk_mul_f32 v[190:191], v[190:191], v[46:47]
	v_pk_mul_f32 v[230:231], v[230:231], v[48:49]
	v_cvt_pk_bf16_f32 v242, v186, v187
	v_cvt_pk_bf16_f32 v243, v188, v189
	v_cvt_pk_bf16_f32 v244, v190, v191
	v_cvt_pk_bf16_f32 v245, v230, v231
	global_store_dwordx4 v[238:239], v[242:245], off sc1
	s_nop 1
	v_lshl_add_u64 v[238:239], v[238:239], 0, s[14:15]
	ds_read_b32 v176, v197 offset:640
	s_waitcnt lgkmcnt(0)
; __device__ __forceinline__ void st16_wt(void* p, u32x4 v) { asm volatile("global_store_dwordx4 %0, %1, off sc1\n\ts_nop 1" :: "v"(p), "v"(v) : "memory"); }
; __device__ __forceinline__ void st16_wt(void* p, f32x4 v) { asm volatile("global_store_dwordx4 %0, %1, off sc1\n\ts_nop 1" :: "v"(p), "v"(v) : "memory"); }
; __device__ __forceinline__ u32x4 pack8(const f32x4& a, const f32x4& b) { u32x4 w; w.x = cvt_pk_bf16(a[0], a[1]); w.y = cvt_pk_bf16(a[2], a[3]); w.z = cvt_pk_bf16(b[0], b[1]); w.w = cvt_pk_bf16(b[2], b[3]); return w; }
;     __device__ __forceinline__ void operator()(const f32x4 (&acc)[2][2][4][2], const Unit& u, int wr, int wc, int fr, int fq) const {
;     ...
;             for (int m = 0; m < 4; ++m) { const int rit = ai * HALF + wr * 64 + m * 16 + fr, row = u.pm * BM + rit; const float r = RST[rit];
;                 f32x4 g[2], vv[2], hv[2];
; #pragma unroll
;                 for (int n = 0; n < 2; ++n) { g[n] = acc[ai][1][m][n] * r; vv[n] = acc[ai][0][m][n] * r;
; #pragma unroll
;                     for (int e = 0; e < 4; ++e) { const float a1 = dpp_mov<0x121>(g[n][e]), a2 = dpp_mov<0x122>(g[n][e]);
;                         const float b1 = m == 0 ? hp1[n][e] : dpp_mov<0x121>(gp[n][e]), b2 = m == 0 ? (fr == 1 ? hp1[n][e] : hp0[n][e]) : dpp_mov<0x122>(gp[n][e]);
;                         const float p1 = fr >= 1 ? a1 : b1, p2 = fr >= 2 ? a2 : b2;
;                         const float cv = bb[n][e] + w0[n][e] * p2 + w1[n][e] * p1 + w2[n][e] * g[n][e];
;                         hv[n][e] = fgelu(cv) * vv[n][e]; } }
;                 if (m == 0 && bnd == 0 && fr < 2) { float* p = fv + ((size_t)u.pm * 2 + fr) * DFF + c0; st16_wt(p, vv[0]); st16_wt(p + 4, vv[1]); float* q = fg + ((size_t)u.pm * 2 + fr) * DFF + c0; st16_wt(q, g[0]); st16_wt(q + 4, g[1]); }
;                 else st16_wt(h + (size_t)row * DFF + c0, pack8(hv[0], hv[1]));
;                 if (m == 3 && bnd == 3 && fr >= 14) { float* p = lg + ((size_t)u.pm * 2 + (fr - 14)) * DFF + c0; st16_wt(p, g[0]); st16_wt(p + 4, g[1]);
;                     if ((u.pm & 7) == 7) { float* q = convout + ((size_t)(u.pm >> 3) * 2 + (fr - 14)) * DFF + c0; *(f32x4*)q = g[0]; *(f32x4*)(q + 4) = g[1]; } }
;                 gp[0] = g[0]; gp[1] = g[1];
;                 asm volatile("" ::: "memory"); }
	v_pk_mul_f32 v[26:27], v[26:27], v[176:177] op_sel_hi:[1,0]
	v_pk_mul_f32 v[28:29], v[28:29], v[176:177] op_sel_hi:[1,0]
	v_pk_mul_f32 v[18:19], v[18:19], v[176:177] op_sel_hi:[1,0]
	v_pk_mul_f32 v[20:21], v[20:21], v[176:177] op_sel_hi:[1,0]
	v_pk_mul_f32 v[30:31], v[30:31], v[176:177] op_sel_hi:[1,0]
	v_pk_mul_f32 v[32:33], v[32:33], v[176:177] op_sel_hi:[1,0]
	v_pk_mul_f32 v[22:23], v[22:23], v[176:177] op_sel_hi:[1,0]
	v_pk_mul_f32 v[24:25], v[24:25], v[176:177] op_sel_hi:[1,0]
	v_cndmask_b32_e64 v202, v26, v58, s[6:7]
	v_cndmask_b32_e64 v203, v27, v59, s[6:7]
	v_cndmask_b32_e64 v204, v28, v60, s[6:7]
	v_cndmask_b32_e64 v205, v29, v61, s[6:7]
	v_cndmask_b32_e64 v206, v18, v42, s[6:7]
	v_cndmask_b32_e64 v207, v19, v43, s[6:7]
	v_cndmask_b32_e64 v208, v20, v44, s[6:7]
	v_cndmask_b32_e64 v209, v21, v45, s[6:7]
	v_cndmask_b32_e64 v210, v26, v58, s[8:9]
	v_cndmask_b32_e64 v211, v27, v59, s[8:9]
	v_cndmask_b32_e64 v212, v28, v60, s[8:9]
	v_cndmask_b32_e64 v213, v29, v61, s[8:9]
	v_cndmask_b32_e64 v214, v18, v42, s[8:9]
	v_cndmask_b32_e64 v215, v19, v43, s[8:9]
	v_cndmask_b32_e64 v216, v20, v44, s[8:9]
	v_cndmask_b32_e64 v217, v21, v45, s[8:9]
	v_pk_fma_f32 v[178:179], v[154:155], v[26:27], v[54:55]
	v_pk_fma_f32 v[180:181], v[156:157], v[28:29], v[56:57]
	v_pk_fma_f32 v[182:183], v[150:151], v[18:19], v[38:39]
	v_pk_fma_f32 v[184:185], v[152:153], v[20:21], v[40:41]
	v_fmac_f32_dpp v178, v202, v158 row_ror:1 row_mask:0xf bank_mask:0xf
	v_fmac_f32_dpp v179, v203, v159 row_ror:1 row_mask:0xf bank_mask:0xf
	v_fmac_f32_dpp v180, v204, v160 row_ror:1 row_mask:0xf bank_mask:0xf
	v_fmac_f32_dpp v181, v205, v161 row_ror:1 row_mask:0xf bank_mask:0xf
	v_fmac_f32_dpp v182, v206, v146 row_ror:1 row_mask:0xf bank_mask:0xf
	v_fmac_f32_dpp v183, v207, v147 row_ror:1 row_mask:0xf bank_mask:0xf
	v_fmac_f32_dpp v184, v208, v148 row_ror:1 row_mask:0xf bank_mask:0xf
	v_fmac_f32_dpp v185, v209, v149 row_ror:1 row_mask:0xf bank_mask:0xf
	v_fmac_f32_dpp v178, v210, v50 row_ror:2 row_mask:0xf bank_mask:0xf
	v_fmac_f32_dpp v179, v211, v51 row_ror:2 row_mask:0xf bank_mask:0xf
	v_fmac_f32_dpp v180, v212, v52 row_ror:2 row_mask:0xf bank_mask:0xf
	v_fmac_f32_dpp v181, v213, v53 row_ror:2 row_mask:0xf bank_mask:0xf
	v_fmac_f32_dpp v182, v214, v34 row_ror:2 row_mask:0xf bank_mask:0xf
	v_fmac_f32_dpp v183, v215, v35 row_ror:2 row_mask:0xf bank_mask:0xf
	v_fmac_f32_dpp v184, v216, v36 row_ror:2 row_mask:0xf bank_mask:0xf
	v_fmac_f32_dpp v185, v217, v37 row_ror:2 row_mask:0xf bank_mask:0xf
	v_pk_mul_f32 v[222:223], v[178:179], v[178:179]
	v_pk_mul_f32 v[224:225], v[180:181], v[180:181]
	v_pk_mul_f32 v[226:227], v[182:183], v[182:183]
	v_pk_mul_f32 v[228:229], v[184:185], v[184:185]
	v_pk_fma_f32 v[222:223], v[222:223], v[234:235], v[232:233]
	v_pk_fma_f32 v[224:225], v[224:225], v[234:235], v[232:233]
	v_pk_fma_f32 v[226:227], v[226:227], v[234:235], v[232:233]
	v_pk_fma_f32 v[228:229], v[228:229], v[234:235], v[232:233]
	v_pk_mul_f32 v[222:223], v[178:179], v[222:223]
	v_pk_mul_f32 v[224:225], v[180:181], v[224:225]
	v_pk_mul_f32 v[226:227], v[182:183], v[226:227]
	v_pk_mul_f32 v[228:229], v[184:185], v[228:229]
	v_exp_f32_e32 v186, v222
	v_exp_f32_e32 v187, v223
	v_exp_f32_e32 v188, v224
	v_exp_f32_e32 v189, v225
	v_exp_f32_e32 v190, v226
	v_exp_f32_e32 v191, v227
	v_exp_f32_e32 v230, v228
	v_exp_f32_e32 v231, v229
	v_pk_add_f32 v[186:187], v[186:187], v[218:219]
	v_pk_add_f32 v[188:189], v[188:189], v[218:219]
	v_pk_add_f32 v[190:191], v[190:191], v[218:219]
	v_pk_add_f32 v[230:231], v[230:231], v[218:219]
	v_rcp_f32_e32 v186, v186
	v_rcp_f32_e32 v187, v187
	v_rcp_f32_e32 v188, v188
	v_rcp_f32_e32 v189, v189
	v_rcp_f32_e32 v190, v190
	v_rcp_f32_e32 v191, v191
	v_rcp_f32_e32 v230, v230
	v_rcp_f32_e32 v231, v231
	v_pk_mul_f32 v[186:187], v[178:179], v[186:187]
	v_pk_mul_f32 v[188:189], v[180:181], v[188:189]
	v_pk_mul_f32 v[190:191], v[182:183], v[190:191]
	v_pk_mul_f32 v[230:231], v[184:185], v[230:231]
	v_pk_mul_f32 v[186:187], v[186:187], v[30:31]
	v_pk_mul_f32 v[188:189], v[188:189], v[32:33]
	v_pk_mul_f32 v[190:191], v[190:191], v[22:23]
	v_pk_mul_f32 v[230:231], v[230:231], v[24:25]
	v_cvt_pk_bf16_f32 v242, v186, v187
	v_cvt_pk_bf16_f32 v243, v188, v189
	v_cvt_pk_bf16_f32 v244, v190, v191
	v_cvt_pk_bf16_f32 v245, v230, v231
	global_store_dwordx4 v[238:239], v[242:245], off sc1
	s_nop 1
	v_lshl_add_u64 v[238:239], v[238:239], 0, s[14:15]
	ds_read_b32 v176, v197 offset:704
	s_waitcnt lgkmcnt(0)
; __device__ __forceinline__ void st16_wt(void* p, u32x4 v) { asm volatile("global_store_dwordx4 %0, %1, off sc1\n\ts_nop 1" :: "v"(p), "v"(v) : "memory"); }
; __device__ __forceinline__ void st16_wt(void* p, f32x4 v) { asm volatile("global_store_dwordx4 %0, %1, off sc1\n\ts_nop 1" :: "v"(p), "v"(v) : "memory"); }
; __device__ __forceinline__ u32x4 pack8(const f32x4& a, const f32x4& b) { u32x4 w; w.x = cvt_pk_bf16(a[0], a[1]); w.y = cvt_pk_bf16(a[2], a[3]); w.z = cvt_pk_bf16(b[0], b[1]); w.w = cvt_pk_bf16(b[2], b[3]); return w; }
;     __device__ __forceinline__ void operator()(const f32x4 (&acc)[2][2][4][2], const Unit& u, int wr, int wc, int fr, int fq) const {
;     ...
;             for (int m = 0; m < 4; ++m) { const int rit = ai * HALF + wr * 64 + m * 16 + fr, row = u.pm * BM + rit; const float r = RST[rit];
;                 f32x4 g[2], vv[2], hv[2];
; #pragma unroll
;                 for (int n = 0; n < 2; ++n) { g[n] = acc[ai][1][m][n] * r; vv[n] = acc[ai][0][m][n] * r;
; #pragma unroll
;                     for (int e = 0; e < 4; ++e) { const float a1 = dpp_mov<0x121>(g[n][e]), a2 = dpp_mov<0x122>(g[n][e]);
;                         const float b1 = m == 0 ? hp1[n][e] : dpp_mov<0x121>(gp[n][e]), b2 = m == 0 ? (fr == 1 ? hp1[n][e] : hp0[n][e]) : dpp_mov<0x122>(gp[n][e]);
;                         const float p1 = fr >= 1 ? a1 : b1, p2 = fr >= 2 ? a2 : b2;
;                         const float cv = bb[n][e] + w0[n][e] * p2 + w1[n][e] * p1 + w2[n][e] * g[n][e];
;                         hv[n][e] = fgelu(cv) * vv[n][e]; } }
;                 if (m == 0 && bnd == 0 && fr < 2) { float* p = fv + ((size_t)u.pm * 2 + fr) * DFF + c0; st16_wt(p, vv[0]); st16_wt(p + 4, vv[1]); float* q = fg + ((size_t)u.pm * 2 + fr) * DFF + c0; st16_wt(q, g[0]); st16_wt(q + 4, g[1]); }
;                 else st16_wt(h + (size_t)row * DFF + c0, pack8(hv[0], hv[1]));
;                 if (m == 3 && bnd == 3 && fr >= 14) { float* p = lg + ((size_t)u.pm * 2 + (fr - 14)) * DFF + c0; st16_wt(p, g[0]); st16_wt(p + 4, g[1]);
;                     if ((u.pm & 7) == 7) { float* q = convout + ((size_t)(u.pm >> 3) * 2 + (fr - 14)) * DFF + c0; *(f32x4*)q = g[0]; *(f32x4*)(q + 4) = g[1]; } }
;                 gp[0] = g[0]; gp[1] = g[1];
;                 asm volatile("" ::: "memory"); }
	v_pk_mul_f32 v[10:11], v[10:11], v[176:177] op_sel_hi:[1,0]
	v_pk_mul_f32 v[12:13], v[12:13], v[176:177] op_sel_hi:[1,0]
	v_pk_mul_f32 v[2:3], v[2:3], v[176:177] op_sel_hi:[1,0]
	v_pk_mul_f32 v[4:5], v[4:5], v[176:177] op_sel_hi:[1,0]
	v_pk_mul_f32 v[14:15], v[14:15], v[176:177] op_sel_hi:[1,0]
	v_pk_mul_f32 v[16:17], v[16:17], v[176:177] op_sel_hi:[1,0]
	v_pk_mul_f32 v[6:7], v[6:7], v[176:177] op_sel_hi:[1,0]
	v_pk_mul_f32 v[8:9], v[8:9], v[176:177] op_sel_hi:[1,0]
	v_cndmask_b32_e64 v202, v10, v26, s[6:7]
	v_cndmask_b32_e64 v203, v11, v27, s[6:7]
	v_cndmask_b32_e64 v204, v12, v28, s[6:7]
	v_cndmask_b32_e64 v205, v13, v29, s[6:7]
	v_cndmask_b32_e64 v206, v2, v18, s[6:7]
	v_cndmask_b32_e64 v207, v3, v19, s[6:7]
	v_cndmask_b32_e64 v208, v4, v20, s[6:7]
	v_cndmask_b32_e64 v209, v5, v21, s[6:7]
	v_cndmask_b32_e64 v210, v10, v26, s[8:9]
	v_cndmask_b32_e64 v211, v11, v27, s[8:9]
	v_cndmask_b32_e64 v212, v12, v28, s[8:9]
	v_cndmask_b32_e64 v213, v13, v29, s[8:9]
	v_cndmask_b32_e64 v214, v2, v18, s[8:9]
	v_cndmask_b32_e64 v215, v3, v19, s[8:9]
	v_cndmask_b32_e64 v216, v4, v20, s[8:9]
	v_cndmask_b32_e64 v217, v5, v21, s[8:9]
	v_pk_fma_f32 v[178:179], v[154:155], v[10:11], v[54:55]
	v_pk_fma_f32 v[180:181], v[156:157], v[12:13], v[56:57]
	v_pk_fma_f32 v[182:183], v[150:151], v[2:3], v[38:39]
	v_pk_fma_f32 v[184:185], v[152:153], v[4:5], v[40:41]
	v_fmac_f32_dpp v178, v202, v158 row_ror:1 row_mask:0xf bank_mask:0xf
	v_fmac_f32_dpp v179, v203, v159 row_ror:1 row_mask:0xf bank_mask:0xf
	v_fmac_f32_dpp v180, v204, v160 row_ror:1 row_mask:0xf bank_mask:0xf
	v_fmac_f32_dpp v181, v205, v161 row_ror:1 row_mask:0xf bank_mask:0xf
	v_fmac_f32_dpp v182, v206, v146 row_ror:1 row_mask:0xf bank_mask:0xf
	v_fmac_f32_dpp v183, v207, v147 row_ror:1 row_mask:0xf bank_mask:0xf
	v_fmac_f32_dpp v184, v208, v148 row_ror:1 row_mask:0xf bank_mask:0xf
	v_fmac_f32_dpp v185, v209, v149 row_ror:1 row_mask:0xf bank_mask:0xf
	v_fmac_f32_dpp v178, v210, v50 row_ror:2 row_mask:0xf bank_mask:0xf
	v_fmac_f32_dpp v179, v211, v51 row_ror:2 row_mask:0xf bank_mask:0xf
	v_fmac_f32_dpp v180, v212, v52 row_ror:2 row_mask:0xf bank_mask:0xf
	v_fmac_f32_dpp v181, v213, v53 row_ror:2 row_mask:0xf bank_mask:0xf
	v_fmac_f32_dpp v182, v214, v34 row_ror:2 row_mask:0xf bank_mask:0xf
	v_fmac_f32_dpp v183, v215, v35 row_ror:2 row_mask:0xf bank_mask:0xf
	v_fmac_f32_dpp v184, v216, v36 row_ror:2 row_mask:0xf bank_mask:0xf
	v_fmac_f32_dpp v185, v217, v37 row_ror:2 row_mask:0xf bank_mask:0xf
	v_pk_mul_f32 v[222:223], v[178:179], v[178:179]
	v_pk_mul_f32 v[224:225], v[180:181], v[180:181]
	v_pk_mul_f32 v[226:227], v[182:183], v[182:183]
	v_pk_mul_f32 v[228:229], v[184:185], v[184:185]
	v_pk_fma_f32 v[222:223], v[222:223], v[234:235], v[232:233]
	v_pk_fma_f32 v[224:225], v[224:225], v[234:235], v[232:233]
	v_pk_fma_f32 v[226:227], v[226:227], v[234:235], v[232:233]
	v_pk_fma_f32 v[228:229], v[228:229], v[234:235], v[232:233]
	v_pk_mul_f32 v[222:223], v[178:179], v[222:223]
	v_pk_mul_f32 v[224:225], v[180:181], v[224:225]
	v_pk_mul_f32 v[226:227], v[182:183], v[226:227]
	v_pk_mul_f32 v[228:229], v[184:185], v[228:229]
	v_exp_f32_e32 v186, v222
	v_exp_f32_e32 v187, v223
	v_exp_f32_e32 v188, v224
	v_exp_f32_e32 v189, v225
	v_exp_f32_e32 v190, v226
	v_exp_f32_e32 v191, v227
	v_exp_f32_e32 v230, v228
	v_exp_f32_e32 v231, v229
	v_pk_add_f32 v[186:187], v[186:187], v[218:219]
	v_pk_add_f32 v[188:189], v[188:189], v[218:219]
	v_pk_add_f32 v[190:191], v[190:191], v[218:219]
	v_pk_add_f32 v[230:231], v[230:231], v[218:219]
	v_rcp_f32_e32 v186, v186
	v_rcp_f32_e32 v187, v187
	v_rcp_f32_e32 v188, v188
	v_rcp_f32_e32 v189, v189
	v_rcp_f32_e32 v190, v190
	v_rcp_f32_e32 v191, v191
	v_rcp_f32_e32 v230, v230
	v_rcp_f32_e32 v231, v231
	v_pk_mul_f32 v[186:187], v[178:179], v[186:187]
	v_pk_mul_f32 v[188:189], v[180:181], v[188:189]
	v_pk_mul_f32 v[190:191], v[182:183], v[190:191]
	v_pk_mul_f32 v[230:231], v[184:185], v[230:231]
	v_pk_mul_f32 v[186:187], v[186:187], v[14:15]
	v_pk_mul_f32 v[188:189], v[188:189], v[16:17]
	v_pk_mul_f32 v[190:191], v[190:191], v[6:7]
	v_pk_mul_f32 v[230:231], v[230:231], v[8:9]
	v_cvt_pk_bf16_f32 v242, v186, v187
	v_cvt_pk_bf16_f32 v243, v188, v189
	v_cvt_pk_bf16_f32 v244, v190, v191
	v_cvt_pk_bf16_f32 v245, v230, v231
	global_store_dwordx4 v[238:239], v[242:245], off sc1
	s_nop 1
	s_cmp_eq_u32 s16, 0
	s_cbranch_scc1 .Lefu_no_lg
	s_mov_b64 s[12:13], exec
	s_and_b64 exec, exec, s[8:9]
	v_add_u32_e32 v0, -14, v200
	v_lshl_add_u32 v198, s40, 1, v0
	s_movk_i32 s17, 0x2c00
	v_mov_b64_e32 v[176:177], s[58:59]
	v_mad_u64_u32 v[176:177], vcc, v198, s17, v[176:177]
	v_lshl_add_u64 v[176:177], v[176:177], 0, v[192:193]
	global_store_dwordx4 v[176:177], v[10:13], off sc1
	s_nop 1
	global_store_dwordx4 v[176:177], v[2:5], off offset:16 sc1
	s_nop 1
	s_and_b32 s17, s40, 7
	s_cmp_lg_u32 s17, 7
	s_cbranch_scc1 .Lefu_no_cs
	s_lshr_b32 s17, s40, 3
	v_lshl_add_u32 v198, s17, 1, v0
	v_readlane_b32 s48, v255, 20
	v_readlane_b32 s49, v255, 21
	s_movk_i32 s17, 0x2c00
	s_nop 1
	v_mov_b64_e32 v[176:177], s[48:49]
	v_mad_u64_u32 v[176:177], vcc, v198, s17, v[176:177]
	v_lshl_add_u64 v[176:177], v[176:177], 0, v[192:193]
	global_store_dwordx4 v[176:177], v[10:13], off
	global_store_dwordx4 v[176:177], v[2:5], off offset:16
.Lefu_no_cs:
	s_mov_b64 exec, s[12:13]
.Lefu_no_lg:
	s_andn2_b64 vcc, exec, s[0:1]
	s_cbranch_vccnz .LBB0_2062
	s_waitcnt vmcnt(0)
	v_mbcnt_lo_u32_b32 v0, -1, 0
	v_mbcnt_hi_u32_b32 v0, -1, v0
	s_nop 0
	v_cmp_eq_u32_e32 vcc, 0, v0
	s_and_saveexec_b64 s[6:7], vcc
	s_cbranch_execz .LBB0_2061
	s_mov_b64 s[8:9], exec
	v_mbcnt_lo_u32_b32 v0, s8, 0
	v_mbcnt_hi_u32_b32 v0, s9, v0
	v_cmp_eq_u32_e32 vcc, 0, v0
	s_and_b64 s[10:11], exec, vcc
	s_mov_b64 exec, s[10:11]
	s_cbranch_execz .LBB0_2061
	s_lshl_b32 s10, s40, 4
	s_andn2_b32 s10, s10, 63
	s_ashr_i32 s11, s10, 31
	s_lshl_b64 s[10:11], s[10:11], 2
	v_readlane_b32 s12, v255, 38
	s_add_u32 s10, s12, s10
	v_readlane_b32 s12, v255, 35
	s_addc_u32 s11, s12, s11
	s_bcnt1_i32_b64 s8, s[8:9]
	v_mov_b32_e32 v0, s8
	global_atomic_add v1, v0, s[10:11]
